# down-GEMM epilogue: first residual row loads and their address math hoisted above the epilogue alignment barrier
# baseline (speedup 1.0000x reference)
.LBB0_826:
	s_add_i32 s91, s4, 2
	s_add_u32 vcc_lo, s36, 0x80
	s_addc_u32 s5, s37, 0
	s_add_i32 s48, 0, 0x10000
	s_cmp_eq_u32 s59, s4
	s_cselect_b32 s5, s43, s5
	s_cselect_b32 s4, s42, vcc_lo
	v_add_u32_e32 v152, s48, v172
	s_cselect_b32 vcc_hi, s53, s88
	s_cselect_b32 vcc_lo, s52, s85
	s_add_i32 s49, 0, 0x14000
	ds_read_b128 v[126:129], v152
	ds_read_b128 v[134:137], v152 offset:1024
	ds_read_b128 v[148:151], v152 offset:2048
	ds_read_b128 v[176:179], v152 offset:3072
	v_add_u32_e32 v152, s49, v172
	ds_read_b128 v[190:193], v152
	ds_read_b128 v[194:197], v152 offset:1024
	ds_read_b128 v[198:201], v152 offset:2048
	ds_read_b128 v[202:205], v152 offset:3072
	v_lshl_add_u64 v[152:153], s[36:37], 0, v[146:147]
	s_add_i32 m0, s8, 0xc000
	ds_read_b128 v[206:209], v174
	ds_read_b128 v[210:213], v174 offset:1024
	ds_read_b128 v[214:217], v174 offset:2048
	ds_read_b128 v[218:221], v174 offset:3072
	ds_read_b128 v[226:229], v174 offset:4096
	ds_read_b128 v[230:233], v174 offset:5120
	ds_read_b128 v[234:237], v174 offset:6144
	ds_read_b128 v[238:241], v174 offset:7168
	global_load_lds_dwordx4 v[152:153], off
	v_lshl_add_u64 v[152:153], s[36:37], 0, v[144:145]
	s_add_i32 m0, s8, 0xe000
	s_nop 0
	global_load_lds_dwordx4 v[152:153], off
	s_waitcnt vmcnt(8)
	s_waitcnt lgkmcnt(0)
	s_barrier
	s_setprio 1
	s_waitcnt lgkmcnt(0)
	v_mfma_f32_16x16x32_bf16 v[130:133], v[126:129], v[206:209], v[130:133]
	v_mfma_f32_16x16x32_bf16 v[122:125], v[148:151], v[206:209], v[122:125]
	v_mfma_f32_16x16x32_bf16 v[110:113], v[126:129], v[214:217], v[110:113]
	v_mfma_f32_16x16x32_bf16 v[106:109], v[148:151], v[214:217], v[106:109]
	v_mfma_f32_16x16x32_bf16 v[94:97], v[126:129], v[226:229], v[94:97]
	v_mfma_f32_16x16x32_bf16 v[90:93], v[148:151], v[226:229], v[90:93]
	v_mfma_f32_16x16x32_bf16 v[78:81], v[126:129], v[234:237], v[78:81]
	v_mfma_f32_16x16x32_bf16 v[74:77], v[148:151], v[234:237], v[74:77]
	v_mfma_f32_16x16x32_bf16 v[130:133], v[134:137], v[210:213], v[130:133]
	v_mfma_f32_16x16x32_bf16 v[122:125], v[176:179], v[210:213], v[122:125]
	v_mfma_f32_16x16x32_bf16 v[110:113], v[134:137], v[218:221], v[110:113]
	v_mfma_f32_16x16x32_bf16 v[106:109], v[176:179], v[218:221], v[106:109]
	v_mfma_f32_16x16x32_bf16 v[94:97], v[134:137], v[230:233], v[94:97]
	v_mfma_f32_16x16x32_bf16 v[90:93], v[176:179], v[230:233], v[90:93]
	v_mfma_f32_16x16x32_bf16 v[78:81], v[134:137], v[238:241], v[78:81]
	v_mfma_f32_16x16x32_bf16 v[74:77], v[176:179], v[238:241], v[74:77]
	s_setprio 0
	s_setprio 1
	v_mfma_f32_16x16x32_bf16 v[118:121], v[190:193], v[206:209], v[118:121]
	v_mfma_f32_16x16x32_bf16 v[114:117], v[198:201], v[206:209], v[114:117]
	v_mfma_f32_16x16x32_bf16 v[102:105], v[190:193], v[214:217], v[102:105]
	v_mfma_f32_16x16x32_bf16 v[98:101], v[198:201], v[214:217], v[98:101]
	v_mfma_f32_16x16x32_bf16 v[86:89], v[190:193], v[226:229], v[86:89]
	v_mfma_f32_16x16x32_bf16 v[82:85], v[198:201], v[226:229], v[82:85]
	v_mfma_f32_16x16x32_bf16 v[70:73], v[190:193], v[234:237], v[70:73]
	v_mfma_f32_16x16x32_bf16 v[66:69], v[198:201], v[234:237], v[66:69]
	v_mfma_f32_16x16x32_bf16 v[118:121], v[194:197], v[210:213], v[118:121]
	v_mfma_f32_16x16x32_bf16 v[114:117], v[202:205], v[210:213], v[114:117]
	v_mfma_f32_16x16x32_bf16 v[102:105], v[194:197], v[218:221], v[102:105]
	v_mfma_f32_16x16x32_bf16 v[98:101], v[202:205], v[218:221], v[98:101]
	v_mfma_f32_16x16x32_bf16 v[86:89], v[194:197], v[230:233], v[86:89]
	v_mfma_f32_16x16x32_bf16 v[82:85], v[202:205], v[230:233], v[82:85]
	v_mfma_f32_16x16x32_bf16 v[70:73], v[194:197], v[238:241], v[70:73]
	v_mfma_f32_16x16x32_bf16 v[66:69], v[202:205], v[238:241], v[66:69]
	s_setprio 0
	s_barrier
	s_add_i32 s48, s48, s7
	v_lshl_add_u64 v[152:153], vcc, 0, v[8:9]
	s_mov_b32 m0, s48
	ds_read_b128 v[206:209], v174 offset:16384
	ds_read_b128 v[210:213], v174 offset:17408
	ds_read_b128 v[214:217], v174 offset:18432
	ds_read_b128 v[218:221], v174 offset:19456
	ds_read_b128 v[226:229], v174 offset:20480
	ds_read_b128 v[230:233], v174 offset:21504
	ds_read_b128 v[234:237], v174 offset:22528
	ds_read_b128 v[238:241], v174 offset:23552
	global_load_lds_dwordx4 v[152:153], off
	s_add_i32 m0, s48, 0x2000
	v_lshl_add_u64 v[180:181], vcc, 0, v[142:143]
	s_add_u32 vcc_lo, vcc_lo, s68
	s_addc_u32 vcc_hi, vcc_hi, 0
	s_add_i32 s48, s49, s7
	global_load_lds_dwordx4 v[180:181], off
	v_lshl_add_u64 v[222:223], vcc, 0, v[8:9]
	s_mov_b32 m0, s48
	v_lshl_add_u64 v[242:243], vcc, 0, v[142:143]
	global_load_lds_dwordx4 v[222:223], off
	s_add_i32 m0, s48, 0x2000
	v_lshl_add_u64 v[244:245], s[4:5], 0, v[138:139]
	global_load_lds_dwordx4 v[242:243], off
	s_mov_b32 m0, s8
	v_lshl_add_u64 v[246:247], s[4:5], 0, v[140:141]
	global_load_lds_dwordx4 v[244:245], off
	s_mov_b32 m0, s9
	s_nop 0
	global_load_lds_dwordx4 v[246:247], off
	s_waitcnt vmcnt(8)
	s_waitcnt lgkmcnt(0)
	s_barrier
	s_setprio 1
	s_waitcnt lgkmcnt(0)
	v_mfma_f32_16x16x32_bf16 v[62:65], v[126:129], v[206:209], v[62:65]
	v_mfma_f32_16x16x32_bf16 v[58:61], v[148:151], v[206:209], v[58:61]
	v_mfma_f32_16x16x32_bf16 v[46:49], v[126:129], v[214:217], v[46:49]
	v_mfma_f32_16x16x32_bf16 v[42:45], v[148:151], v[214:217], v[42:45]
	v_mfma_f32_16x16x32_bf16 v[30:33], v[126:129], v[226:229], v[30:33]
	v_mfma_f32_16x16x32_bf16 v[26:29], v[148:151], v[226:229], v[26:29]
	v_mfma_f32_16x16x32_bf16 v[14:17], v[126:129], v[234:237], v[14:17]
	v_mfma_f32_16x16x32_bf16 v[10:13], v[148:151], v[234:237], v[10:13]
	v_mfma_f32_16x16x32_bf16 v[62:65], v[134:137], v[210:213], v[62:65]
	v_mfma_f32_16x16x32_bf16 v[58:61], v[176:179], v[210:213], v[58:61]
	v_mfma_f32_16x16x32_bf16 v[46:49], v[134:137], v[218:221], v[46:49]
	v_mfma_f32_16x16x32_bf16 v[42:45], v[176:179], v[218:221], v[42:45]
	v_mfma_f32_16x16x32_bf16 v[30:33], v[134:137], v[230:233], v[30:33]
	v_mfma_f32_16x16x32_bf16 v[26:29], v[176:179], v[230:233], v[26:29]
	v_mfma_f32_16x16x32_bf16 v[14:17], v[134:137], v[238:241], v[14:17]
	v_mfma_f32_16x16x32_bf16 v[10:13], v[176:179], v[238:241], v[10:13]
	s_setprio 0
	s_setprio 1
	v_mfma_f32_16x16x32_bf16 v[54:57], v[190:193], v[206:209], v[54:57]
	v_mfma_f32_16x16x32_bf16 v[50:53], v[198:201], v[206:209], v[50:53]
	v_mfma_f32_16x16x32_bf16 v[38:41], v[190:193], v[214:217], v[38:41]
	v_mfma_f32_16x16x32_bf16 v[34:37], v[198:201], v[214:217], v[34:37]
	v_mfma_f32_16x16x32_bf16 v[22:25], v[190:193], v[226:229], v[22:25]
	v_mfma_f32_16x16x32_bf16 v[18:21], v[198:201], v[226:229], v[18:21]
	v_mfma_f32_16x16x32_bf16 v[4:7], v[190:193], v[234:237], v[4:7]
	v_mfma_f32_16x16x32_bf16 v[0:3], v[198:201], v[234:237], v[0:3]
	v_mfma_f32_16x16x32_bf16 v[54:57], v[194:197], v[210:213], v[54:57]
	v_mfma_f32_16x16x32_bf16 v[50:53], v[202:205], v[210:213], v[50:53]
	v_mfma_f32_16x16x32_bf16 v[38:41], v[194:197], v[218:221], v[38:41]
	v_mfma_f32_16x16x32_bf16 v[34:37], v[202:205], v[218:221], v[34:37]
	v_mfma_f32_16x16x32_bf16 v[22:25], v[194:197], v[230:233], v[22:25]
	v_mfma_f32_16x16x32_bf16 v[18:21], v[202:205], v[230:233], v[18:21]
	v_mfma_f32_16x16x32_bf16 v[4:7], v[194:197], v[238:241], v[4:7]
	v_mfma_f32_16x16x32_bf16 v[0:3], v[202:205], v[238:241], v[0:3]
	s_setprio 0
	s_barrier
	s_add_i32 s48, 0, 0x18000
	v_add_u32_e32 v154, s48, v172
	s_add_i32 s49, 0, 0x1c000
	ds_read_b128 v[126:129], v154
	ds_read_b128 v[134:137], v154 offset:1024
	ds_read_b128 v[148:151], v154 offset:2048
	ds_read_b128 v[176:179], v154 offset:3072
	v_add_u32_e32 v154, s49, v172
	ds_read_b128 v[190:193], v154
	ds_read_b128 v[194:197], v154 offset:1024
	ds_read_b128 v[198:201], v154 offset:2048
	ds_read_b128 v[202:205], v154 offset:3072
	s_add_u32 s4, s4, s68
	s_addc_u32 s5, s5, 0
	s_mov_b32 m0, s54
	v_lshl_add_u64 v[248:249], s[4:5], 0, v[138:139]
	ds_read_b128 v[206:209], v174 offset:32768
	ds_read_b128 v[210:213], v174 offset:33792
	ds_read_b128 v[214:217], v174 offset:34816
	ds_read_b128 v[218:221], v174 offset:35840
	ds_read_b128 v[226:229], v174 offset:36864
	ds_read_b128 v[230:233], v174 offset:37888
	ds_read_b128 v[234:237], v174 offset:38912
	ds_read_b128 v[238:241], v174 offset:39936
	global_load_lds_dwordx4 v[248:249], off
	v_lshl_add_u64 v[248:249], s[4:5], 0, v[140:141]
	s_mov_b32 m0, s55
	s_nop 0
	global_load_lds_dwordx4 v[248:249], off
	s_waitcnt vmcnt(8)
	s_waitcnt lgkmcnt(0)
	s_barrier
	s_setprio 1
	s_waitcnt lgkmcnt(0)
	v_mfma_f32_16x16x32_bf16 v[130:133], v[126:129], v[206:209], v[130:133]
	v_mfma_f32_16x16x32_bf16 v[122:125], v[148:151], v[206:209], v[122:125]
	v_mfma_f32_16x16x32_bf16 v[110:113], v[126:129], v[214:217], v[110:113]
	v_mfma_f32_16x16x32_bf16 v[106:109], v[148:151], v[214:217], v[106:109]
	v_mfma_f32_16x16x32_bf16 v[94:97], v[126:129], v[226:229], v[94:97]
	v_mfma_f32_16x16x32_bf16 v[90:93], v[148:151], v[226:229], v[90:93]
	v_mfma_f32_16x16x32_bf16 v[78:81], v[126:129], v[234:237], v[78:81]
	v_mfma_f32_16x16x32_bf16 v[74:77], v[148:151], v[234:237], v[74:77]
	v_mfma_f32_16x16x32_bf16 v[130:133], v[134:137], v[210:213], v[130:133]
	v_mfma_f32_16x16x32_bf16 v[122:125], v[176:179], v[210:213], v[122:125]
	v_mfma_f32_16x16x32_bf16 v[110:113], v[134:137], v[218:221], v[110:113]
	v_mfma_f32_16x16x32_bf16 v[106:109], v[176:179], v[218:221], v[106:109]
	v_mfma_f32_16x16x32_bf16 v[94:97], v[134:137], v[230:233], v[94:97]
	v_mfma_f32_16x16x32_bf16 v[90:93], v[176:179], v[230:233], v[90:93]
	v_mfma_f32_16x16x32_bf16 v[78:81], v[134:137], v[238:241], v[78:81]
	v_mfma_f32_16x16x32_bf16 v[74:77], v[176:179], v[238:241], v[74:77]
	s_setprio 0
	s_setprio 1
	v_mfma_f32_16x16x32_bf16 v[118:121], v[190:193], v[206:209], v[118:121]
	v_mfma_f32_16x16x32_bf16 v[114:117], v[198:201], v[206:209], v[114:117]
	v_mfma_f32_16x16x32_bf16 v[102:105], v[190:193], v[214:217], v[102:105]
	v_mfma_f32_16x16x32_bf16 v[98:101], v[198:201], v[214:217], v[98:101]
	v_mfma_f32_16x16x32_bf16 v[86:89], v[190:193], v[226:229], v[86:89]
	v_mfma_f32_16x16x32_bf16 v[82:85], v[198:201], v[226:229], v[82:85]
	v_mfma_f32_16x16x32_bf16 v[70:73], v[190:193], v[234:237], v[70:73]
	v_mfma_f32_16x16x32_bf16 v[66:69], v[198:201], v[234:237], v[66:69]
	v_mfma_f32_16x16x32_bf16 v[118:121], v[194:197], v[210:213], v[118:121]
	v_mfma_f32_16x16x32_bf16 v[114:117], v[202:205], v[210:213], v[114:117]
	v_mfma_f32_16x16x32_bf16 v[102:105], v[194:197], v[218:221], v[102:105]
	v_mfma_f32_16x16x32_bf16 v[98:101], v[202:205], v[218:221], v[98:101]
	v_mfma_f32_16x16x32_bf16 v[86:89], v[194:197], v[230:233], v[86:89]
	v_mfma_f32_16x16x32_bf16 v[82:85], v[202:205], v[230:233], v[82:85]
	v_mfma_f32_16x16x32_bf16 v[70:73], v[194:197], v[238:241], v[70:73]
	v_mfma_f32_16x16x32_bf16 v[66:69], v[202:205], v[238:241], v[66:69]
	s_setprio 0
	s_barrier
	s_add_i32 s4, s48, s7
	v_lshl_add_u64 v[152:153], v[152:153], 0, s[94:95]
	s_mov_b32 m0, s4
	ds_read_b128 v[206:209], v174 offset:49152
	ds_read_b128 v[210:213], v174 offset:50176
	ds_read_b128 v[214:217], v174 offset:51200
	ds_read_b128 v[218:221], v174 offset:52224
	ds_read_b128 v[226:229], v174 offset:53248
	ds_read_b128 v[230:233], v174 offset:54272
	ds_read_b128 v[234:237], v174 offset:55296
	ds_read_b128 v[238:241], v174 offset:56320
	global_load_lds_dwordx4 v[152:153], off
	v_lshl_add_u64 v[152:153], v[180:181], 0, s[94:95]
	s_add_i32 m0, s4, 0x2000
	s_add_i32 s4, s49, s7
	global_load_lds_dwordx4 v[152:153], off
	v_lshl_add_u64 v[152:153], v[222:223], 0, s[94:95]
	s_mov_b32 m0, s4
	s_nop 0
	global_load_lds_dwordx4 v[152:153], off
	v_lshl_add_u64 v[152:153], v[242:243], 0, s[94:95]
	s_add_i32 m0, s4, 0x2000
	s_nop 0
	global_load_lds_dwordx4 v[152:153], off
	v_lshl_add_u64 v[152:153], v[244:245], 0, s[94:95]
	s_mov_b32 m0, s57
	s_nop 0
	global_load_lds_dwordx4 v[152:153], off
	v_lshl_add_u64 v[152:153], v[246:247], 0, s[94:95]
	s_mov_b32 m0, s58
	s_nop 0
	global_load_lds_dwordx4 v[152:153], off
	s_waitcnt vmcnt(8)
	s_waitcnt lgkmcnt(0)
	s_barrier
	s_setprio 1
	s_waitcnt lgkmcnt(0)
	v_mfma_f32_16x16x32_bf16 v[62:65], v[126:129], v[206:209], v[62:65]
	v_mfma_f32_16x16x32_bf16 v[58:61], v[148:151], v[206:209], v[58:61]
	v_mfma_f32_16x16x32_bf16 v[46:49], v[126:129], v[214:217], v[46:49]
	v_mfma_f32_16x16x32_bf16 v[42:45], v[148:151], v[214:217], v[42:45]
	v_mfma_f32_16x16x32_bf16 v[30:33], v[126:129], v[226:229], v[30:33]
	v_mfma_f32_16x16x32_bf16 v[26:29], v[148:151], v[226:229], v[26:29]
	v_mfma_f32_16x16x32_bf16 v[14:17], v[126:129], v[234:237], v[14:17]
	v_mfma_f32_16x16x32_bf16 v[10:13], v[148:151], v[234:237], v[10:13]
	v_mfma_f32_16x16x32_bf16 v[62:65], v[134:137], v[210:213], v[62:65]
	v_mfma_f32_16x16x32_bf16 v[58:61], v[176:179], v[210:213], v[58:61]
	v_mfma_f32_16x16x32_bf16 v[46:49], v[134:137], v[218:221], v[46:49]
	v_mfma_f32_16x16x32_bf16 v[42:45], v[176:179], v[218:221], v[42:45]
	v_mfma_f32_16x16x32_bf16 v[30:33], v[134:137], v[230:233], v[30:33]
	v_mfma_f32_16x16x32_bf16 v[26:29], v[176:179], v[230:233], v[26:29]
	v_mfma_f32_16x16x32_bf16 v[14:17], v[134:137], v[238:241], v[14:17]
	v_mfma_f32_16x16x32_bf16 v[10:13], v[176:179], v[238:241], v[10:13]
	s_setprio 0
	s_setprio 1
	v_mfma_f32_16x16x32_bf16 v[54:57], v[190:193], v[206:209], v[54:57]
	v_mfma_f32_16x16x32_bf16 v[50:53], v[198:201], v[206:209], v[50:53]
	v_mfma_f32_16x16x32_bf16 v[38:41], v[190:193], v[214:217], v[38:41]
	v_mfma_f32_16x16x32_bf16 v[34:37], v[198:201], v[214:217], v[34:37]
	v_mfma_f32_16x16x32_bf16 v[22:25], v[190:193], v[226:229], v[22:25]
	v_mfma_f32_16x16x32_bf16 v[18:21], v[198:201], v[226:229], v[18:21]
	v_mfma_f32_16x16x32_bf16 v[4:7], v[190:193], v[234:237], v[4:7]
	v_mfma_f32_16x16x32_bf16 v[0:3], v[198:201], v[234:237], v[0:3]
	v_mfma_f32_16x16x32_bf16 v[54:57], v[194:197], v[210:213], v[54:57]
	v_mfma_f32_16x16x32_bf16 v[50:53], v[202:205], v[210:213], v[50:53]
	v_mfma_f32_16x16x32_bf16 v[38:41], v[194:197], v[218:221], v[38:41]
	v_mfma_f32_16x16x32_bf16 v[34:37], v[202:205], v[218:221], v[34:37]
	v_mfma_f32_16x16x32_bf16 v[22:25], v[194:197], v[230:233], v[22:25]
	v_mfma_f32_16x16x32_bf16 v[18:21], v[202:205], v[230:233], v[18:21]
	v_mfma_f32_16x16x32_bf16 v[4:7], v[194:197], v[238:241], v[4:7]
	v_mfma_f32_16x16x32_bf16 v[0:3], v[202:205], v[238:241], v[0:3]
	s_setprio 0
	s_barrier
	s_add_u32 s85, s85, 0x100
	s_addc_u32 s88, s88, 0
	s_add_u32 s36, s36, 0x100
	s_addc_u32 s37, s37, 0
	s_cmp_ge_u32 s91, s56
	s_mov_b32 s4, s91
	s_cbranch_scc0 .LBB0_826
	v_lshl_add_u32 v150, s16, 8, v171
	v_lshl_or_b32 v148, s17, 8, v173
	v_ashrrev_i32_e32 v151, 31, v150
	v_lshlrev_b64 v[126:127], 12, v[150:151]
	v_ashrrev_i32_e32 v149, 31, v148
	v_lshl_add_u64 v[126:127], s[14:15], 0, v[126:127]
	v_lshlrev_b64 v[128:129], 1, v[148:149]
	v_lshl_add_u64 v[180:181], v[126:127], 0, v[128:129]
	global_load_dwordx4 v[176:179], v[180:181], off
	global_load_dwordx4 v[190:193], v[180:181], off offset:256
	v_or_b32_e32 v126, 16, v150
	v_ashrrev_i32_e32 v127, 31, v126
	v_lshlrev_b64 v[126:127], 12, v[126:127]
	v_lshl_add_u64 v[126:127], s[14:15], 0, v[126:127]
	v_lshl_add_u64 v[152:153], v[126:127], 0, v[128:129]
	global_load_dwordx4 v[134:137], v[152:153], off
	global_load_dwordx4 v[126:129], v[152:153], off offset:256
	s_and_b64 vcc, exec, s[46:47]
	s_cbranch_vccz .LBB0_829
	s_barrier
.LBB0_829:
	s_waitcnt vmcnt(0)
	v_lshlrev_b32_e32 v194, 16, v176
	v_and_b32_e32 v195, 0xffff0000, v176
	v_lshlrev_b32_e32 v176, 16, v177
	v_and_b32_e32 v177, 0xffff0000, v177
	v_pk_fma_f32 v[132:133], s[34:35], v[132:133], v[176:177]
	v_pk_fma_f32 v[176:177], s[22:23], v[130:131], v[194:195]
	v_cvt_pk_bf16_f32 v131, v132, v133
	v_mul_f32_e32 v154, v177, v177
	v_mul_f32_e32 v133, v133, v133
	v_fmac_f32_e32 v154, v176, v176
	v_fmac_f32_e32 v133, v132, v132
	v_add_f32_e32 v154, v154, v133
	v_lshlrev_b32_e32 v132, 16, v178
	v_and_b32_e32 v133, 0xffff0000, v178
	v_cvt_pk_bf16_f32 v130, v176, v177
	v_lshlrev_b32_e32 v176, 16, v179
	v_and_b32_e32 v177, 0xffff0000, v179
	v_pk_fma_f32 v[122:123], s[22:23], v[122:123], v[132:133]
	v_pk_fma_f32 v[124:125], s[34:35], v[124:125], v[176:177]
	v_cvt_pk_bf16_f32 v132, v122, v123
	v_mul_f32_e32 v123, v123, v123
	v_fmac_f32_e32 v123, v122, v122
	v_mul_f32_e32 v122, v125, v125
	v_fmac_f32_e32 v122, v124, v124
	v_add_f32_e32 v122, v123, v122
	v_cvt_pk_bf16_f32 v133, v124, v125
	v_add_f32_e32 v154, v154, v122
	v_lshlrev_b32_e32 v122, 16, v190
	v_and_b32_e32 v123, 0xffff0000, v190
	v_lshlrev_b32_e32 v124, 16, v191
	v_and_b32_e32 v125, 0xffff0000, v191
	v_pk_fma_f32 v[120:121], s[34:35], v[120:121], v[124:125]
	v_pk_fma_f32 v[122:123], s[22:23], v[118:119], v[122:123]
	v_cvt_pk_bf16_f32 v119, v120, v121
	v_cvt_pk_bf16_f32 v118, v122, v123
	v_mul_f32_e32 v123, v123, v123
	v_mul_f32_e32 v121, v121, v121
	v_fmac_f32_e32 v123, v122, v122
	v_fmac_f32_e32 v121, v120, v120
	v_add_f32_e32 v120, v123, v121
	v_add_f32_e32 v124, v154, v120
	v_lshlrev_b32_e32 v120, 16, v192
	v_and_b32_e32 v121, 0xffff0000, v192
	v_lshlrev_b32_e32 v122, 16, v193
	v_and_b32_e32 v123, 0xffff0000, v193
	v_pk_fma_f32 v[114:115], s[22:23], v[114:115], v[120:121]
	v_pk_fma_f32 v[116:117], s[34:35], v[116:117], v[122:123]
	v_cvt_pk_bf16_f32 v120, v114, v115
	v_mul_f32_e32 v115, v115, v115
	v_fmac_f32_e32 v115, v114, v114
	v_mul_f32_e32 v114, v117, v117
	v_cvt_pk_bf16_f32 v121, v116, v117
	v_fmac_f32_e32 v114, v116, v116
	v_and_b32_e32 v116, 64, v184
	v_add_f32_e32 v114, v115, v114
	v_xor_b32_e32 v115, 16, v184
	v_add_u32_e32 v116, 64, v116
	v_cmp_lt_i32_e32 vcc, v115, v116
	global_store_dwordx4 v[180:181], v[130:133], off
	v_add_f32_e32 v114, v114, v124
	v_cndmask_b32_e32 v115, v184, v115, vcc
	v_lshlrev_b32_e32 v130, 2, v115
	ds_bpermute_b32 v115, v130, v114
	v_lshl_add_u64 v[122:123], v[150:151], 3, s[44:45]
	global_store_dwordx4 v[180:181], v[118:121], off offset:256
	s_waitcnt lgkmcnt(0)
	v_add_f32_e32 v114, v114, v115
	v_xor_b32_e32 v115, 32, v184
	v_cmp_lt_i32_e32 vcc, v115, v116
	s_nop 1
	v_cndmask_b32_e32 v115, v184, v115, vcc
	v_lshlrev_b32_e32 v131, 2, v115
	ds_bpermute_b32 v115, v131, v114
	s_and_saveexec_b64 s[4:5], s[38:39]
	s_flbit_i32_b32 s85, 0
	s_cbranch_execz .LBB0_831
	s_waitcnt lgkmcnt(0)
	v_add_f32_e32 v114, v114, v115
	v_floor_f32_e32 v116, v114
	v_sub_f32_e32 v114, v114, v116
	v_mul_f32_e32 v114, 0x4f800000, v114
	v_cvt_u32_f32_e32 v115, v116
	v_cvt_u32_f32_e32 v114, v114
	global_atomic_add_x2 v[122:123], v[114:115], off
